# idle-slot deferral layout 4: same deferred work as layout 3, rebalanced between the long (W1/WinA exit) and short (FFN-up 9th round) idle slots with item/row sub-ranges
# baseline (speedup 1.0000x reference)
.LBB0_412:
	s_waitcnt vmcnt(0)
	v_readlane_b32 s86, v255, 26
	v_readlane_b32 s54, v255, 36
	v_readlane_b32 s87, v255, 27
	v_readlane_b32 s55, v255, 37
	s_barrier
	s_mov_b64 s[98:99], exec
	s_mov_b64 exec, -1
	v_readlane_b32 s2, v254, 0
	v_readlane_b32 s3, v255, 24
	s_load_dword s4, s[86:87], 0xc0
	s_waitcnt lgkmcnt(0)
	s_cmp_eq_u32 s3, 1
	s_cbranch_scc1 .Ldm8_go
	s_branch .Ldm8_done

.Ldm8_all:
	v_readfirstlane_b32 s5, v0
	s_lshr_b32 s5, s5, 6
	s_lshl_b32 s2, s2, 3
	s_add_u32 s2, s2, s5
	s_lshl_b32 s92, s4, 3
	v_mbcnt_lo_u32_b32 v41, -1, 0
	v_mbcnt_hi_u32_b32 v41, -1, v41
	v_lshrrev_b32_e32 v42, 3, v41
	v_and_b32_e32 v43, 7, v41
	v_lshlrev_b32_e32 v44, 13, v42
	v_lshl_add_u32 v44, v43, 4, v44
	v_add_u32_e32 v45, 0x10000, v44
	v_add_u32_e32 v46, 0x20000, v44
	v_add_u32_e32 v47, 0x30000, v44
	v_add_u32_e32 v48, 0x40000, v44
	v_add_u32_e32 v49, 0x50000, v44
	v_add_u32_e32 v50, 0x60000, v44
	v_add_u32_e32 v51, 0x70000, v44
	s_lshl_b32 s49, s5, 14
	v_mul_u32_u24_e32 v52, 0x84, v42
	v_lshl_add_u32 v52, v43, 4, v52
	v_add_u32_e32 v52, s49, v52
	v_mul_u32_u24_e32 v53, 0x420, v43
	v_lshl_add_u32 v53, v42, 2, v53
	v_add_u32_e32 v53, s49, v53
	v_lshlrev_b32_e32 v54, 14, v42
	v_lshl_add_u32 v54, v43, 4, v54
	v_add_u32_e32 v55, 0x20000, v54
	v_add_u32_e32 v56, 0x40000, v54
	v_add_u32_e32 v57, 0x60000, v54
	s_mov_b32 s83, 0
.Ldm8_disp:
	s_cmp_eq_u32 s83, 0
	s_cbranch_scc0 .Ldm8_nx0
	s_add_u32 s83, s83, 1
	s_cmp_eq_u32 s3, 1
	s_cbranch_scc0 .Ldm8_disp
	s_mov_b32 s69, 2
	s_mov_b32 s91, 0x0
	s_mov_b32 s93, 0x2000
	s_branch .Ldm8_job

.Ldm8_job:
	s_add_u32 s91, s91, s2
	s_cmp_ge_u32 s91, s93
	s_cbranch_scc1 .Ldm8_disp
	s_load_dwordx2 s[6:7], s[86:87], 0x98
	s_load_dwordx2 s[88:89], s[86:87], 0xb0
	s_lshl_b32 s48, s69, 26
	s_waitcnt lgkmcnt(0)
	s_add_u32 s6, s6, s48
	s_addc_u32 s7, s7, 0
	s_lshl_b32 s48, s69, 25
	s_add_u32 s88, s88, 0x76b32000
	s_addc_u32 s89, s89, 0
	s_add_u32 s88, s88, s48
	s_addc_u32 s89, s89, 0
	s_lshr_b32 s72, s91, 6
	s_and_b32 s73, s91, 63
	s_lshl_b32 s56, s72, 19
	s_lshl_b32 s57, s73, 7
	s_add_u32 s56, s56, s57
	s_add_u32 s50, s6, s56
	s_addc_u32 s51, s7, 0
	global_load_dwordx4 v[58:61], v44, s[50:51] nt
	global_load_dwordx4 v[62:65], v45, s[50:51] nt
	global_load_dwordx4 v[66:69], v46, s[50:51] nt
	global_load_dwordx4 v[70:73], v47, s[50:51] nt
	global_load_dwordx4 v[74:77], v48, s[50:51] nt
	global_load_dwordx4 v[78:81], v49, s[50:51] nt
	global_load_dwordx4 v[82:85], v50, s[50:51] nt
	global_load_dwordx4 v[86:89], v51, s[50:51] nt
	s_add_u32 s71, s91, s92
	s_cmp_ge_u32 s71, s93
	s_cbranch_scc1 .Ldm8_first0
	s_lshr_b32 s72, s71, 6
	s_and_b32 s73, s71, 63
	s_lshl_b32 s56, s72, 19
	s_lshl_b32 s57, s73, 7
	s_add_u32 s56, s56, s57
	s_add_u32 s50, s6, s56
	s_addc_u32 s51, s7, 0
	global_load_dwordx4 v[90:93], v44, s[50:51] nt
	global_load_dwordx4 v[94:97], v45, s[50:51] nt
	global_load_dwordx4 v[98:101], v46, s[50:51] nt
	global_load_dwordx4 v[102:105], v47, s[50:51] nt
	global_load_dwordx4 v[106:109], v48, s[50:51] nt
	global_load_dwordx4 v[110:113], v49, s[50:51] nt
	global_load_dwordx4 v[114:117], v50, s[50:51] nt
	global_load_dwordx4 v[118:121], v51, s[50:51] nt
	s_waitcnt vmcnt(8)
	s_branch .Ldm8_loop

.Ldm8_loop:
	s_lshr_b32 s72, s91, 6
	s_and_b32 s73, s91, 63
	s_lshl_b32 s58, s73, 19
	s_lshl_b32 s59, s72, 7
	s_add_u32 s58, s58, s59
	ds_write_b32 v52, v58 offset:0
	ds_write_b32 v52, v59 offset:4
	ds_write_b32 v52, v60 offset:8
	ds_write_b32 v52, v61 offset:12
	ds_write_b32 v52, v62 offset:1056
	ds_write_b32 v52, v63 offset:1060
	ds_write_b32 v52, v64 offset:1064
	ds_write_b32 v52, v65 offset:1068
	ds_write_b32 v52, v66 offset:2112
	ds_write_b32 v52, v67 offset:2116
	ds_write_b32 v52, v68 offset:2120
	ds_write_b32 v52, v69 offset:2124
	ds_write_b32 v52, v70 offset:3168
	ds_write_b32 v52, v71 offset:3172
	ds_write_b32 v52, v72 offset:3176
	ds_write_b32 v52, v73 offset:3180
	ds_write_b32 v52, v74 offset:4224
	ds_write_b32 v52, v75 offset:4228
	ds_write_b32 v52, v76 offset:4232
	ds_write_b32 v52, v77 offset:4236
	ds_write_b32 v52, v78 offset:5280
	ds_write_b32 v52, v79 offset:5284
	ds_write_b32 v52, v80 offset:5288
	ds_write_b32 v52, v81 offset:5292
	ds_write_b32 v52, v82 offset:6336
	ds_write_b32 v52, v83 offset:6340
	ds_write_b32 v52, v84 offset:6344
	ds_write_b32 v52, v85 offset:6348
	ds_write_b32 v52, v86 offset:7392
	ds_write_b32 v52, v87 offset:7396
	ds_write_b32 v52, v88 offset:7400
	ds_write_b32 v52, v89 offset:7404
	s_waitcnt lgkmcnt(0)
	s_add_u32 s91, s71, s92
	s_cmp_ge_u32 s91, s93
	s_cbranch_scc1 .Ldm8_nopfa
	s_lshr_b32 s72, s91, 6
	s_and_b32 s73, s91, 63
	s_lshl_b32 s56, s72, 19
	s_lshl_b32 s57, s73, 7
	s_add_u32 s56, s56, s57
	s_add_u32 s50, s6, s56
	s_addc_u32 s51, s7, 0
	global_load_dwordx4 v[58:61], v44, s[50:51] nt
	global_load_dwordx4 v[62:65], v45, s[50:51] nt
	global_load_dwordx4 v[66:69], v46, s[50:51] nt
	global_load_dwordx4 v[70:73], v47, s[50:51] nt
	global_load_dwordx4 v[74:77], v48, s[50:51] nt
	global_load_dwordx4 v[78:81], v49, s[50:51] nt
	global_load_dwordx4 v[82:85], v50, s[50:51] nt
	global_load_dwordx4 v[86:89], v51, s[50:51] nt
.Ldm8_nopfa:
	ds_read2_b32 v[122:123], v53 offset0:0 offset1:33
	ds_read2_b32 v[124:125], v53 offset0:66 offset1:99
	ds_read2_b32 v[126:127], v53 offset0:132 offset1:165
	ds_read2_b32 v[128:129], v53 offset0:198 offset1:231
	ds_read2_b32 v[130:131], v53 offset0:8 offset1:41
	ds_read2_b32 v[132:133], v53 offset0:74 offset1:107
	ds_read2_b32 v[134:135], v53 offset0:140 offset1:173
	ds_read2_b32 v[136:137], v53 offset0:206 offset1:239
	ds_read2_b32 v[138:139], v53 offset0:16 offset1:49
	ds_read2_b32 v[140:141], v53 offset0:82 offset1:115
	ds_read2_b32 v[142:143], v53 offset0:148 offset1:181
	ds_read2_b32 v[144:145], v53 offset0:214 offset1:247
	ds_read2_b32 v[146:147], v53 offset0:24 offset1:57
	ds_read2_b32 v[148:149], v53 offset0:90 offset1:123
	ds_read2_b32 v[180:181], v53 offset0:156 offset1:189
	ds_read2_b32 v[182:183], v53 offset0:222 offset1:255
	s_waitcnt lgkmcnt(0)
	v_cvt_pk_bf16_f32 v184, v122, v123
	v_cvt_pk_bf16_f32 v185, v124, v125
	v_cvt_pk_bf16_f32 v186, v126, v127
	v_cvt_pk_bf16_f32 v187, v128, v129
	v_cvt_pk_bf16_f32 v188, v130, v131
	v_cvt_pk_bf16_f32 v189, v132, v133
	v_cvt_pk_bf16_f32 v190, v134, v135
	v_cvt_pk_bf16_f32 v191, v136, v137
	v_cvt_pk_bf16_f32 v192, v138, v139
	v_cvt_pk_bf16_f32 v193, v140, v141
	v_cvt_pk_bf16_f32 v194, v142, v143
	v_cvt_pk_bf16_f32 v195, v144, v145
	v_cvt_pk_bf16_f32 v196, v146, v147
	v_cvt_pk_bf16_f32 v197, v148, v149
	v_cvt_pk_bf16_f32 v198, v180, v181
	v_cvt_pk_bf16_f32 v199, v182, v183
	v_add_u32_e32 v200, s58, v54
	v_add_u32_e32 v201, s58, v55
	v_add_u32_e32 v202, s58, v56
	v_add_u32_e32 v203, s58, v57
	global_store_dwordx4 v200, v[184:187], s[88:89]
	global_store_dwordx4 v201, v[188:191], s[88:89]
	global_store_dwordx4 v202, v[192:195], s[88:89]
	global_store_dwordx4 v203, v[196:199], s[88:89]
	s_cmp_ge_u32 s71, s93
	s_cbranch_scc1 .Ldm8_jobend
	s_cmp_ge_u32 s91, s93
	s_cbranch_scc1 .Ldm8_w4a
	s_waitcnt vmcnt(12)
	s_branch .Ldm8_goa

.Ldm8_goa:
	s_lshr_b32 s72, s71, 6
	s_and_b32 s73, s71, 63
	s_lshl_b32 s58, s73, 19
	s_lshl_b32 s59, s72, 7
	s_add_u32 s58, s58, s59
	ds_write_b32 v52, v90 offset:0
	ds_write_b32 v52, v91 offset:4
	ds_write_b32 v52, v92 offset:8
	ds_write_b32 v52, v93 offset:12
	ds_write_b32 v52, v94 offset:1056
	ds_write_b32 v52, v95 offset:1060
	ds_write_b32 v52, v96 offset:1064
	ds_write_b32 v52, v97 offset:1068
	ds_write_b32 v52, v98 offset:2112
	ds_write_b32 v52, v99 offset:2116
	ds_write_b32 v52, v100 offset:2120
	ds_write_b32 v52, v101 offset:2124
	ds_write_b32 v52, v102 offset:3168
	ds_write_b32 v52, v103 offset:3172
	ds_write_b32 v52, v104 offset:3176
	ds_write_b32 v52, v105 offset:3180
	ds_write_b32 v52, v106 offset:4224
	ds_write_b32 v52, v107 offset:4228
	ds_write_b32 v52, v108 offset:4232
	ds_write_b32 v52, v109 offset:4236
	ds_write_b32 v52, v110 offset:5280
	ds_write_b32 v52, v111 offset:5284
	ds_write_b32 v52, v112 offset:5288
	ds_write_b32 v52, v113 offset:5292
	ds_write_b32 v52, v114 offset:6336
	ds_write_b32 v52, v115 offset:6340
	ds_write_b32 v52, v116 offset:6344
	ds_write_b32 v52, v117 offset:6348
	ds_write_b32 v52, v118 offset:7392
	ds_write_b32 v52, v119 offset:7396
	ds_write_b32 v52, v120 offset:7400
	ds_write_b32 v52, v121 offset:7404
	s_waitcnt lgkmcnt(0)
	s_add_u32 s71, s91, s92
	s_cmp_ge_u32 s71, s93
	s_cbranch_scc1 .Ldm8_nopfb
	s_lshr_b32 s72, s71, 6
	s_and_b32 s73, s71, 63
	s_lshl_b32 s56, s72, 19
	s_lshl_b32 s57, s73, 7
	s_add_u32 s56, s56, s57
	s_add_u32 s50, s6, s56
	s_addc_u32 s51, s7, 0
	global_load_dwordx4 v[90:93], v44, s[50:51] nt
	global_load_dwordx4 v[94:97], v45, s[50:51] nt
	global_load_dwordx4 v[98:101], v46, s[50:51] nt
	global_load_dwordx4 v[102:105], v47, s[50:51] nt
	global_load_dwordx4 v[106:109], v48, s[50:51] nt
	global_load_dwordx4 v[110:113], v49, s[50:51] nt
	global_load_dwordx4 v[114:117], v50, s[50:51] nt
	global_load_dwordx4 v[118:121], v51, s[50:51] nt
.Ldm8_nopfb:
	ds_read2_b32 v[122:123], v53 offset0:0 offset1:33
	ds_read2_b32 v[124:125], v53 offset0:66 offset1:99
	ds_read2_b32 v[126:127], v53 offset0:132 offset1:165
	ds_read2_b32 v[128:129], v53 offset0:198 offset1:231
	ds_read2_b32 v[130:131], v53 offset0:8 offset1:41
	ds_read2_b32 v[132:133], v53 offset0:74 offset1:107
	ds_read2_b32 v[134:135], v53 offset0:140 offset1:173
	ds_read2_b32 v[136:137], v53 offset0:206 offset1:239
	ds_read2_b32 v[138:139], v53 offset0:16 offset1:49
	ds_read2_b32 v[140:141], v53 offset0:82 offset1:115
	ds_read2_b32 v[142:143], v53 offset0:148 offset1:181
	ds_read2_b32 v[144:145], v53 offset0:214 offset1:247
	ds_read2_b32 v[146:147], v53 offset0:24 offset1:57
	ds_read2_b32 v[148:149], v53 offset0:90 offset1:123
	ds_read2_b32 v[180:181], v53 offset0:156 offset1:189
	ds_read2_b32 v[182:183], v53 offset0:222 offset1:255
	s_waitcnt lgkmcnt(0)
	v_cvt_pk_bf16_f32 v184, v122, v123
	v_cvt_pk_bf16_f32 v185, v124, v125
	v_cvt_pk_bf16_f32 v186, v126, v127
	v_cvt_pk_bf16_f32 v187, v128, v129
	v_cvt_pk_bf16_f32 v188, v130, v131
	v_cvt_pk_bf16_f32 v189, v132, v133
	v_cvt_pk_bf16_f32 v190, v134, v135
	v_cvt_pk_bf16_f32 v191, v136, v137
	v_cvt_pk_bf16_f32 v192, v138, v139
	v_cvt_pk_bf16_f32 v193, v140, v141
	v_cvt_pk_bf16_f32 v194, v142, v143
	v_cvt_pk_bf16_f32 v195, v144, v145
	v_cvt_pk_bf16_f32 v196, v146, v147
	v_cvt_pk_bf16_f32 v197, v148, v149
	v_cvt_pk_bf16_f32 v198, v180, v181
	v_cvt_pk_bf16_f32 v199, v182, v183
	v_add_u32_e32 v200, s58, v54
	v_add_u32_e32 v201, s58, v55
	v_add_u32_e32 v202, s58, v56
	v_add_u32_e32 v203, s58, v57
	global_store_dwordx4 v200, v[184:187], s[88:89]
	global_store_dwordx4 v201, v[188:191], s[88:89]
	global_store_dwordx4 v202, v[192:195], s[88:89]
	global_store_dwordx4 v203, v[196:199], s[88:89]
	s_cmp_ge_u32 s91, s93
	s_cbranch_scc1 .Ldm8_jobend
	s_cmp_ge_u32 s71, s93
	s_cbranch_scc1 .Ldm8_w4b
	s_waitcnt vmcnt(12)
	s_branch .Ldm8_gob

.Ldm8_gob:
	s_branch .Ldm8_loop
.Ldm8_jobend:
	s_branch .Ldm8_disp
.Ldm8_done:
	s_mov_b64 exec, s[98:99]
	s_mov_b64 s[98:99], exec
	s_mov_b64 exec, -1
	v_readlane_b32 s2, v254, 0
	v_readlane_b32 s3, v255, 24
	s_load_dword s4, s[86:87], 0xc0
	s_waitcnt lgkmcnt(0)
	s_cmp_eq_u32 s3, 1
	s_cbranch_scc1 .Ldm7_go
	s_branch .Ldm7_done

.Ldm7_all:
	v_readfirstlane_b32 s5, v0
	s_lshr_b32 s5, s5, 6
	s_lshl_b32 s2, s2, 3
	s_add_u32 s2, s2, s5
	s_lshl_b32 s92, s4, 3
	v_mbcnt_lo_u32_b32 v41, -1, 0
	v_mbcnt_hi_u32_b32 v41, -1, v41
	v_lshrrev_b32_e32 v42, 3, v41
	v_and_b32_e32 v43, 7, v41
	v_lshlrev_b32_e32 v44, 15, v42
	v_lshl_add_u32 v44, v43, 4, v44
	v_add_u32_e32 v45, 0x40000, v44
	v_add_u32_e32 v46, 0x80000, v44
	v_add_u32_e32 v47, 0xc0000, v44
	v_add_u32_e32 v48, 0x100000, v44
	v_add_u32_e32 v49, 0x140000, v44
	v_add_u32_e32 v50, 0x180000, v44
	v_add_u32_e32 v51, 0x1c0000, v44
	s_lshl_b32 s49, s5, 14
	v_mul_u32_u24_e32 v52, 0x84, v42
	v_lshl_add_u32 v52, v43, 4, v52
	v_add_u32_e32 v52, s49, v52
	v_mul_u32_u24_e32 v53, 0x420, v43
	v_lshl_add_u32 v53, v42, 2, v53
	v_add_u32_e32 v53, s49, v53
	v_lshlrev_b32_e32 v54, 12, v42
	v_lshl_add_u32 v54, v43, 4, v54
	v_add_u32_e32 v55, 0x8000, v54
	v_add_u32_e32 v56, 0x10000, v54
	v_add_u32_e32 v57, 0x18000, v54
	v_lshlrev_b32_e32 v204, 2, v42
	s_mov_b32 s83, 0

.Ldm7_job:
	s_add_u32 s91, s91, s2
	s_cmp_ge_u32 s91, s93
	s_cbranch_scc1 .Ldm7_disp
	s_load_dwordx2 s[6:7], s[86:87], 0x90
	s_load_dwordx2 s[88:89], s[86:87], 0xb0
	s_load_dwordx2 s[74:75], s[86:87], 0x88
	s_lshl_b32 s48, s69, 26
	s_waitcnt lgkmcnt(0)
	s_add_u32 s6, s6, s48
	s_addc_u32 s7, s7, 0
	s_lshl_b32 s48, s69, 25
	s_add_u32 s88, s88, 0x6eb32000
	s_addc_u32 s89, s89, 0
	s_add_u32 s88, s88, s48
	s_addc_u32 s89, s89, 0
	s_lshl_b32 s48, s69, 13
	s_add_u32 s74, s74, s48
	s_addc_u32 s75, s75, 0
	s_lshr_b32 s72, s91, 8
	s_and_b32 s73, s91, 255
	s_lshl_b32 s56, s72, 21
	s_lshl_b32 s57, s73, 7
	s_add_u32 s56, s56, s57
	s_add_u32 s50, s6, s56
	s_addc_u32 s51, s7, 0
	global_load_dwordx4 v[58:61], v44, s[50:51] nt
	global_load_dwordx4 v[62:65], v45, s[50:51] nt
	global_load_dwordx4 v[66:69], v46, s[50:51] nt
	global_load_dwordx4 v[70:73], v47, s[50:51] nt
	global_load_dwordx4 v[74:77], v48, s[50:51] nt
	global_load_dwordx4 v[78:81], v49, s[50:51] nt
	global_load_dwordx4 v[82:85], v50, s[50:51] nt
	global_load_dwordx4 v[86:89], v51, s[50:51] nt
	s_lshl_b32 s56, s72, 8
	s_add_u32 s50, s74, s56
	s_addc_u32 s51, s75, 0
	global_load_dword v230, v204, s[50:51] offset:0
	global_load_dword v231, v204, s[50:51] offset:32
	global_load_dword v232, v204, s[50:51] offset:64
	global_load_dword v233, v204, s[50:51] offset:96
	global_load_dword v234, v204, s[50:51] offset:128
	global_load_dword v235, v204, s[50:51] offset:160
	global_load_dword v236, v204, s[50:51] offset:192
	global_load_dword v237, v204, s[50:51] offset:224
	s_add_u32 s71, s91, s92
	s_cmp_ge_u32 s71, s93
	s_cbranch_scc1 .Ldm7_first0
	s_lshr_b32 s72, s71, 8
	s_and_b32 s73, s71, 255
	s_lshl_b32 s56, s72, 21
	s_lshl_b32 s57, s73, 7
	s_add_u32 s56, s56, s57
	s_add_u32 s50, s6, s56
	s_addc_u32 s51, s7, 0
	global_load_dwordx4 v[90:93], v44, s[50:51] nt
	global_load_dwordx4 v[94:97], v45, s[50:51] nt
	global_load_dwordx4 v[98:101], v46, s[50:51] nt
	global_load_dwordx4 v[102:105], v47, s[50:51] nt
	global_load_dwordx4 v[106:109], v48, s[50:51] nt
	global_load_dwordx4 v[110:113], v49, s[50:51] nt
	global_load_dwordx4 v[114:117], v50, s[50:51] nt
	global_load_dwordx4 v[118:121], v51, s[50:51] nt
	s_lshl_b32 s56, s72, 8
	s_add_u32 s50, s74, s56
	s_addc_u32 s51, s75, 0
	global_load_dword v238, v204, s[50:51] offset:0
	global_load_dword v239, v204, s[50:51] offset:32
	global_load_dword v240, v204, s[50:51] offset:64
	global_load_dword v241, v204, s[50:51] offset:96
	global_load_dword v242, v204, s[50:51] offset:128
	global_load_dword v243, v204, s[50:51] offset:160
	global_load_dword v244, v204, s[50:51] offset:192
	global_load_dword v245, v204, s[50:51] offset:224
	s_waitcnt vmcnt(16)
	s_branch .Ldm7_loop

.Ldm7_loop:
	s_lshr_b32 s72, s91, 8
	s_and_b32 s73, s91, 255
	s_lshl_b32 s58, s73, 17
	s_lshl_b32 s59, s72, 7
	s_add_u32 s58, s58, s59
	v_mul_f32_e32 v58, v58, v230
	v_mul_f32_e32 v59, v59, v230
	v_mul_f32_e32 v60, v60, v230
	v_mul_f32_e32 v61, v61, v230
	v_mul_f32_e32 v62, v62, v231
	v_mul_f32_e32 v63, v63, v231
	v_mul_f32_e32 v64, v64, v231
	v_mul_f32_e32 v65, v65, v231
	v_mul_f32_e32 v66, v66, v232
	v_mul_f32_e32 v67, v67, v232
	v_mul_f32_e32 v68, v68, v232
	v_mul_f32_e32 v69, v69, v232
	v_mul_f32_e32 v70, v70, v233
	v_mul_f32_e32 v71, v71, v233
	v_mul_f32_e32 v72, v72, v233
	v_mul_f32_e32 v73, v73, v233
	v_mul_f32_e32 v74, v74, v234
	v_mul_f32_e32 v75, v75, v234
	v_mul_f32_e32 v76, v76, v234
	v_mul_f32_e32 v77, v77, v234
	v_mul_f32_e32 v78, v78, v235
	v_mul_f32_e32 v79, v79, v235
	v_mul_f32_e32 v80, v80, v235
	v_mul_f32_e32 v81, v81, v235
	v_mul_f32_e32 v82, v82, v236
	v_mul_f32_e32 v83, v83, v236
	v_mul_f32_e32 v84, v84, v236
	v_mul_f32_e32 v85, v85, v236
	v_mul_f32_e32 v86, v86, v237
	v_mul_f32_e32 v87, v87, v237
	v_mul_f32_e32 v88, v88, v237
	v_mul_f32_e32 v89, v89, v237
	ds_write_b32 v52, v58 offset:0
	ds_write_b32 v52, v59 offset:4
	ds_write_b32 v52, v60 offset:8
	ds_write_b32 v52, v61 offset:12
	ds_write_b32 v52, v62 offset:1056
	ds_write_b32 v52, v63 offset:1060
	ds_write_b32 v52, v64 offset:1064
	ds_write_b32 v52, v65 offset:1068
	ds_write_b32 v52, v66 offset:2112
	ds_write_b32 v52, v67 offset:2116
	ds_write_b32 v52, v68 offset:2120
	ds_write_b32 v52, v69 offset:2124
	ds_write_b32 v52, v70 offset:3168
	ds_write_b32 v52, v71 offset:3172
	ds_write_b32 v52, v72 offset:3176
	ds_write_b32 v52, v73 offset:3180
	ds_write_b32 v52, v74 offset:4224
	ds_write_b32 v52, v75 offset:4228
	ds_write_b32 v52, v76 offset:4232
	ds_write_b32 v52, v77 offset:4236
	ds_write_b32 v52, v78 offset:5280
	ds_write_b32 v52, v79 offset:5284
	ds_write_b32 v52, v80 offset:5288
	ds_write_b32 v52, v81 offset:5292
	ds_write_b32 v52, v82 offset:6336
	ds_write_b32 v52, v83 offset:6340
	ds_write_b32 v52, v84 offset:6344
	ds_write_b32 v52, v85 offset:6348
	ds_write_b32 v52, v86 offset:7392
	ds_write_b32 v52, v87 offset:7396
	ds_write_b32 v52, v88 offset:7400
	ds_write_b32 v52, v89 offset:7404
	s_waitcnt lgkmcnt(0)
	s_add_u32 s91, s71, s92
	s_cmp_ge_u32 s91, s93
	s_cbranch_scc1 .Ldm7_nopfa
	s_lshr_b32 s72, s91, 8
	s_and_b32 s73, s91, 255
	s_lshl_b32 s56, s72, 21
	s_lshl_b32 s57, s73, 7
	s_add_u32 s56, s56, s57
	s_add_u32 s50, s6, s56
	s_addc_u32 s51, s7, 0
	global_load_dwordx4 v[58:61], v44, s[50:51] nt
	global_load_dwordx4 v[62:65], v45, s[50:51] nt
	global_load_dwordx4 v[66:69], v46, s[50:51] nt
	global_load_dwordx4 v[70:73], v47, s[50:51] nt
	global_load_dwordx4 v[74:77], v48, s[50:51] nt
	global_load_dwordx4 v[78:81], v49, s[50:51] nt
	global_load_dwordx4 v[82:85], v50, s[50:51] nt
	global_load_dwordx4 v[86:89], v51, s[50:51] nt
	s_lshl_b32 s56, s72, 8
	s_add_u32 s50, s74, s56
	s_addc_u32 s51, s75, 0
	global_load_dword v230, v204, s[50:51] offset:0
	global_load_dword v231, v204, s[50:51] offset:32
	global_load_dword v232, v204, s[50:51] offset:64
	global_load_dword v233, v204, s[50:51] offset:96
	global_load_dword v234, v204, s[50:51] offset:128
	global_load_dword v235, v204, s[50:51] offset:160
	global_load_dword v236, v204, s[50:51] offset:192
	global_load_dword v237, v204, s[50:51] offset:224
.Ldm7_nopfa:
	ds_read2_b32 v[122:123], v53 offset0:0 offset1:33
	ds_read2_b32 v[124:125], v53 offset0:66 offset1:99
	ds_read2_b32 v[126:127], v53 offset0:132 offset1:165
	ds_read2_b32 v[128:129], v53 offset0:198 offset1:231
	ds_read2_b32 v[130:131], v53 offset0:8 offset1:41
	ds_read2_b32 v[132:133], v53 offset0:74 offset1:107
	ds_read2_b32 v[134:135], v53 offset0:140 offset1:173
	ds_read2_b32 v[136:137], v53 offset0:206 offset1:239
	ds_read2_b32 v[138:139], v53 offset0:16 offset1:49
	ds_read2_b32 v[140:141], v53 offset0:82 offset1:115
	ds_read2_b32 v[142:143], v53 offset0:148 offset1:181
	ds_read2_b32 v[144:145], v53 offset0:214 offset1:247
	ds_read2_b32 v[146:147], v53 offset0:24 offset1:57
	ds_read2_b32 v[148:149], v53 offset0:90 offset1:123
	ds_read2_b32 v[180:181], v53 offset0:156 offset1:189
	ds_read2_b32 v[182:183], v53 offset0:222 offset1:255
	s_waitcnt lgkmcnt(0)
	v_cvt_pk_bf16_f32 v184, v122, v123
	v_cvt_pk_bf16_f32 v185, v124, v125
	v_cvt_pk_bf16_f32 v186, v126, v127
	v_cvt_pk_bf16_f32 v187, v128, v129
	v_cvt_pk_bf16_f32 v188, v130, v131
	v_cvt_pk_bf16_f32 v189, v132, v133
	v_cvt_pk_bf16_f32 v190, v134, v135
	v_cvt_pk_bf16_f32 v191, v136, v137
	v_cvt_pk_bf16_f32 v192, v138, v139
	v_cvt_pk_bf16_f32 v193, v140, v141
	v_cvt_pk_bf16_f32 v194, v142, v143
	v_cvt_pk_bf16_f32 v195, v144, v145
	v_cvt_pk_bf16_f32 v196, v146, v147
	v_cvt_pk_bf16_f32 v197, v148, v149
	v_cvt_pk_bf16_f32 v198, v180, v181
	v_cvt_pk_bf16_f32 v199, v182, v183
	v_add_u32_e32 v200, s58, v54
	v_add_u32_e32 v201, s58, v55
	v_add_u32_e32 v202, s58, v56
	v_add_u32_e32 v203, s58, v57
	global_store_dwordx4 v200, v[184:187], s[88:89]
	global_store_dwordx4 v201, v[188:191], s[88:89]
	global_store_dwordx4 v202, v[192:195], s[88:89]
	global_store_dwordx4 v203, v[196:199], s[88:89]
	s_cmp_ge_u32 s71, s93
	s_cbranch_scc1 .Ldm7_jobend
	s_cmp_ge_u32 s91, s93
	s_cbranch_scc1 .Ldm7_w4a
	s_waitcnt vmcnt(20)
	s_branch .Ldm7_goa

.Ldm7_goa:
	s_lshr_b32 s72, s71, 8
	s_and_b32 s73, s71, 255
	s_lshl_b32 s58, s73, 17
	s_lshl_b32 s59, s72, 7
	s_add_u32 s58, s58, s59
	v_mul_f32_e32 v90, v90, v238
	v_mul_f32_e32 v91, v91, v238
	v_mul_f32_e32 v92, v92, v238
	v_mul_f32_e32 v93, v93, v238
	v_mul_f32_e32 v94, v94, v239
	v_mul_f32_e32 v95, v95, v239
	v_mul_f32_e32 v96, v96, v239
	v_mul_f32_e32 v97, v97, v239
	v_mul_f32_e32 v98, v98, v240
	v_mul_f32_e32 v99, v99, v240
	v_mul_f32_e32 v100, v100, v240
	v_mul_f32_e32 v101, v101, v240
	v_mul_f32_e32 v102, v102, v241
	v_mul_f32_e32 v103, v103, v241
	v_mul_f32_e32 v104, v104, v241
	v_mul_f32_e32 v105, v105, v241
	v_mul_f32_e32 v106, v106, v242
	v_mul_f32_e32 v107, v107, v242
	v_mul_f32_e32 v108, v108, v242
	v_mul_f32_e32 v109, v109, v242
	v_mul_f32_e32 v110, v110, v243
	v_mul_f32_e32 v111, v111, v243
	v_mul_f32_e32 v112, v112, v243
	v_mul_f32_e32 v113, v113, v243
	v_mul_f32_e32 v114, v114, v244
	v_mul_f32_e32 v115, v115, v244
	v_mul_f32_e32 v116, v116, v244
	v_mul_f32_e32 v117, v117, v244
	v_mul_f32_e32 v118, v118, v245
	v_mul_f32_e32 v119, v119, v245
	v_mul_f32_e32 v120, v120, v245
	v_mul_f32_e32 v121, v121, v245
	ds_write_b32 v52, v90 offset:0
	ds_write_b32 v52, v91 offset:4
	ds_write_b32 v52, v92 offset:8
	ds_write_b32 v52, v93 offset:12
	ds_write_b32 v52, v94 offset:1056
	ds_write_b32 v52, v95 offset:1060
	ds_write_b32 v52, v96 offset:1064
	ds_write_b32 v52, v97 offset:1068
	ds_write_b32 v52, v98 offset:2112
	ds_write_b32 v52, v99 offset:2116
	ds_write_b32 v52, v100 offset:2120
	ds_write_b32 v52, v101 offset:2124
	ds_write_b32 v52, v102 offset:3168
	ds_write_b32 v52, v103 offset:3172
	ds_write_b32 v52, v104 offset:3176
	ds_write_b32 v52, v105 offset:3180
	ds_write_b32 v52, v106 offset:4224
	ds_write_b32 v52, v107 offset:4228
	ds_write_b32 v52, v108 offset:4232
	ds_write_b32 v52, v109 offset:4236
	ds_write_b32 v52, v110 offset:5280
	ds_write_b32 v52, v111 offset:5284
	ds_write_b32 v52, v112 offset:5288
	ds_write_b32 v52, v113 offset:5292
	ds_write_b32 v52, v114 offset:6336
	ds_write_b32 v52, v115 offset:6340
	ds_write_b32 v52, v116 offset:6344
	ds_write_b32 v52, v117 offset:6348
	ds_write_b32 v52, v118 offset:7392
	ds_write_b32 v52, v119 offset:7396
	ds_write_b32 v52, v120 offset:7400
	ds_write_b32 v52, v121 offset:7404
	s_waitcnt lgkmcnt(0)
	s_add_u32 s71, s91, s92
	s_cmp_ge_u32 s71, s93
	s_cbranch_scc1 .Ldm7_nopfb
	s_lshr_b32 s72, s71, 8
	s_and_b32 s73, s71, 255
	s_lshl_b32 s56, s72, 21
	s_lshl_b32 s57, s73, 7
	s_add_u32 s56, s56, s57
	s_add_u32 s50, s6, s56
	s_addc_u32 s51, s7, 0
	global_load_dwordx4 v[90:93], v44, s[50:51] nt
	global_load_dwordx4 v[94:97], v45, s[50:51] nt
	global_load_dwordx4 v[98:101], v46, s[50:51] nt
	global_load_dwordx4 v[102:105], v47, s[50:51] nt
	global_load_dwordx4 v[106:109], v48, s[50:51] nt
	global_load_dwordx4 v[110:113], v49, s[50:51] nt
	global_load_dwordx4 v[114:117], v50, s[50:51] nt
	global_load_dwordx4 v[118:121], v51, s[50:51] nt
	s_lshl_b32 s56, s72, 8
	s_add_u32 s50, s74, s56
	s_addc_u32 s51, s75, 0
	global_load_dword v238, v204, s[50:51] offset:0
	global_load_dword v239, v204, s[50:51] offset:32
	global_load_dword v240, v204, s[50:51] offset:64
	global_load_dword v241, v204, s[50:51] offset:96
	global_load_dword v242, v204, s[50:51] offset:128
	global_load_dword v243, v204, s[50:51] offset:160
	global_load_dword v244, v204, s[50:51] offset:192
	global_load_dword v245, v204, s[50:51] offset:224
.Ldm7_nopfb:
	ds_read2_b32 v[122:123], v53 offset0:0 offset1:33
	ds_read2_b32 v[124:125], v53 offset0:66 offset1:99
	ds_read2_b32 v[126:127], v53 offset0:132 offset1:165
	ds_read2_b32 v[128:129], v53 offset0:198 offset1:231
	ds_read2_b32 v[130:131], v53 offset0:8 offset1:41
	ds_read2_b32 v[132:133], v53 offset0:74 offset1:107
	ds_read2_b32 v[134:135], v53 offset0:140 offset1:173
	ds_read2_b32 v[136:137], v53 offset0:206 offset1:239
	ds_read2_b32 v[138:139], v53 offset0:16 offset1:49
	ds_read2_b32 v[140:141], v53 offset0:82 offset1:115
	ds_read2_b32 v[142:143], v53 offset0:148 offset1:181
	ds_read2_b32 v[144:145], v53 offset0:214 offset1:247
	ds_read2_b32 v[146:147], v53 offset0:24 offset1:57
	ds_read2_b32 v[148:149], v53 offset0:90 offset1:123
	ds_read2_b32 v[180:181], v53 offset0:156 offset1:189
	ds_read2_b32 v[182:183], v53 offset0:222 offset1:255
	s_waitcnt lgkmcnt(0)
	v_cvt_pk_bf16_f32 v184, v122, v123
	v_cvt_pk_bf16_f32 v185, v124, v125
	v_cvt_pk_bf16_f32 v186, v126, v127
	v_cvt_pk_bf16_f32 v187, v128, v129
	v_cvt_pk_bf16_f32 v188, v130, v131
	v_cvt_pk_bf16_f32 v189, v132, v133
	v_cvt_pk_bf16_f32 v190, v134, v135
	v_cvt_pk_bf16_f32 v191, v136, v137
	v_cvt_pk_bf16_f32 v192, v138, v139
	v_cvt_pk_bf16_f32 v193, v140, v141
	v_cvt_pk_bf16_f32 v194, v142, v143
	v_cvt_pk_bf16_f32 v195, v144, v145
	v_cvt_pk_bf16_f32 v196, v146, v147
	v_cvt_pk_bf16_f32 v197, v148, v149
	v_cvt_pk_bf16_f32 v198, v180, v181
	v_cvt_pk_bf16_f32 v199, v182, v183
	v_add_u32_e32 v200, s58, v54
	v_add_u32_e32 v201, s58, v55
	v_add_u32_e32 v202, s58, v56
	v_add_u32_e32 v203, s58, v57
	global_store_dwordx4 v200, v[184:187], s[88:89]
	global_store_dwordx4 v201, v[188:191], s[88:89]
	global_store_dwordx4 v202, v[192:195], s[88:89]
	global_store_dwordx4 v203, v[196:199], s[88:89]
	s_cmp_ge_u32 s91, s93
	s_cbranch_scc1 .Ldm7_jobend
	s_cmp_ge_u32 s71, s93
	s_cbranch_scc1 .Ldm7_w4b
	s_waitcnt vmcnt(20)
	s_branch .Ldm7_gob

.Ldm7_gob:
	s_branch .Ldm7_loop
.Ldm7_jobend:
	s_branch .Ldm7_disp
.Ldm7_done:
	s_mov_b64 exec, s[98:99]
	s_mov_b64 s[98:99], exec
	s_mov_b64 exec, -1
	v_readlane_b32 s2, v254, 0
	v_readlane_b32 s3, v255, 24
	s_load_dword s4, s[86:87], 0xc0
	s_load_dwordx2 s[6:7], s[86:87], 0x10
	s_load_dwordx2 s[88:89], s[86:87], 0xb0
	s_waitcnt lgkmcnt(0)
	s_cmp_eq_u32 s3, 1
	s_cbranch_scc0 .Ldmc_sel0
	s_mov_b32 s91, 0x20000
	s_mov_b32 s79, 0x24000
	s_branch .Ldmc_go

.Ldmc_go:
	s_cmp_eq_u32 s4, 0x100
	s_cbranch_scc0 .Ldmc_all
	s_cmp_lt_u32 s2, 96
	s_cbranch_scc1 .Ldmc_done
	s_sub_u32 s2, s2, 96
	s_movk_i32 s4, 160
.Ldmc_all:
	v_readfirstlane_b32 s5, v0
	s_lshr_b32 s5, s5, 6
	s_lshl_b32 s2, s2, 3
	s_add_u32 s2, s2, s5
	s_lshl_b32 s92, s4, 3
	s_add_u32 s91, s91, s2
	s_add_u32 s88, s88, 0x27b32000
	s_addc_u32 s89, s89, 0
	v_mbcnt_lo_u32_b32 v41, -1, 0
	v_mbcnt_hi_u32_b32 v41, -1, v41
	v_lshlrev_b32_e32 v42, 5, v41
	v_lshlrev_b32_e32 v43, 4, v41
	s_cmp_ge_u32 s91, s79
	s_cbranch_scc1 .Ldmc_done

.LBB0_975:
	s_waitcnt vmcnt(0)
	v_readlane_b32 s54, v255, 36
	v_readlane_b32 s55, v255, 37
	s_barrier
	s_mov_b64 s[98:99], exec
	s_mov_b64 exec, -1
	v_readlane_b32 s2, v254, 0
	v_readlane_b32 s3, v255, 24
	s_load_dword s4, s[86:87], 0xc0
	s_waitcnt lgkmcnt(0)
	s_cmp_eq_u32 s3, 0
	s_cbranch_scc1 .Ldl8_go
	s_branch .Ldl8_done

.Ldl8_disp:
	s_cmp_eq_u32 s83, 0
	s_cbranch_scc0 .Ldl8_nx0
	s_add_u32 s83, s83, 1
	s_cmp_eq_u32 s3, 0
	s_cbranch_scc0 .Ldl8_disp
	s_mov_b32 s69, 0
	s_mov_b32 s91, 0x0
	s_mov_b32 s93, 0x2000
	s_branch .Ldl8_job

.Ldl8_gob:
	s_branch .Ldl8_loop
.Ldl8_jobend:
	s_branch .Ldl8_disp
.Ldl8_done:
	s_mov_b64 exec, s[98:99]
	s_mov_b64 s[98:99], exec
	s_mov_b64 exec, -1
	v_readlane_b32 s2, v254, 0
	v_readlane_b32 s3, v255, 24
	s_load_dword s4, s[86:87], 0xc0
	s_waitcnt lgkmcnt(0)
	s_cmp_eq_u32 s3, 0
	s_cbranch_scc1 .Ldl7_go
	s_cmp_eq_u32 s3, 2
	s_cbranch_scc1 .Ldl7_go
	s_branch .Ldl7_done

.Ldl7_nx0:
	s_cmp_eq_u32 s83, 1
	s_cbranch_scc0 .Ldl7_nx1
	s_add_u32 s83, s83, 1
	s_cmp_eq_u32 s3, 0
	s_cbranch_scc0 .Ldl7_disp
	s_mov_b32 s69, 1
	s_mov_b32 s91, 0x0
	s_mov_b32 s93, 0x1000
	s_branch .Ldl7_job
.Ldl7_nx1:
	s_cmp_eq_u32 s83, 2
	s_cbranch_scc0 .Ldl7_nx2
	s_add_u32 s83, s83, 1
	s_cmp_eq_u32 s3, 2
	s_cbranch_scc0 .Ldl7_disp
	s_mov_b32 s69, 3
	s_mov_b32 s91, 0x0
	s_mov_b32 s93, 0x1000
	s_branch .Ldl7_job

.Ldl7_gob:
	s_branch .Ldl7_loop
.Ldl7_jobend:
	s_branch .Ldl7_disp
.Ldl7_done:
	s_mov_b64 exec, s[98:99]
	s_mov_b64 s[98:99], exec
	s_mov_b64 exec, -1
	v_readlane_b32 s2, v254, 0
	v_readlane_b32 s3, v255, 24
	s_load_dword s4, s[86:87], 0xc0
	s_load_dwordx2 s[6:7], s[86:87], 0x10
	s_load_dwordx2 s[88:89], s[86:87], 0xb0
	s_waitcnt lgkmcnt(0)
	s_cmp_eq_u32 s3, 2
	s_cbranch_scc0 .Ldlc_sel0
	s_mov_b32 s91, 0x30000
	s_mov_b32 s79, 0x40000
	s_branch .Ldlc_go

.LBB0_1964:
	s_waitcnt vmcnt(0)
	v_readlane_b32 s86, v255, 26
	v_readlane_b32 s87, v255, 27
	s_barrier
	s_mov_b64 s[98:99], exec
	s_mov_b64 exec, -1
	v_readlane_b32 s2, v254, 0
	v_readlane_b32 s3, v255, 24
	s_load_dword s4, s[86:87], 0xc0
	s_waitcnt lgkmcnt(0)
	s_cmp_eq_u32 s3, 0
	s_cbranch_scc1 .Ldj8_go
	s_cmp_eq_u32 s3, 2
	s_cbranch_scc1 .Ldj8_go
	s_branch .Ldj8_done

.Ldj8_disp:
	s_cmp_eq_u32 s83, 0
	s_cbranch_scc0 .Ldj8_nx0
	s_add_u32 s83, s83, 1
	s_cmp_eq_u32 s3, 0
	s_cbranch_scc0 .Ldj8_disp
	s_mov_b32 s69, 1
	s_mov_b32 s91, 0x0
	s_mov_b32 s93, 0x2000
	s_branch .Ldj8_job
.Ldj8_nx0:
	s_cmp_eq_u32 s83, 1
	s_cbranch_scc0 .Ldj8_nx1
	s_add_u32 s83, s83, 1
	s_cmp_eq_u32 s3, 2
	s_cbranch_scc0 .Ldj8_disp
	s_mov_b32 s69, 3
	s_mov_b32 s91, 0x0
	s_mov_b32 s93, 0x2000
	s_branch .Ldj8_job

.Ldj8_gob:
	s_branch .Ldj8_loop
.Ldj8_jobend:
	s_branch .Ldj8_disp

.Ldj7_disp:
	s_cmp_eq_u32 s83, 0
	s_cbranch_scc0 .Ldj7_nx0
	s_add_u32 s83, s83, 1
	s_cmp_eq_u32 s3, 0
	s_cbranch_scc0 .Ldj7_disp
	s_mov_b32 s69, 1
	s_mov_b32 s91, 0x1000
	s_mov_b32 s93, 0x2000
	s_branch .Ldj7_job
.Ldj7_nx0:
	s_cmp_eq_u32 s83, 1
	s_cbranch_scc0 .Ldj7_nx1
	s_add_u32 s83, s83, 1
	s_cmp_eq_u32 s3, 2
	s_cbranch_scc0 .Ldj7_disp
	s_mov_b32 s69, 3
	s_mov_b32 s91, 0x1000
	s_mov_b32 s93, 0x2000
	s_branch .Ldj7_job

.Ldj7_gob:
	s_branch .Ldj7_loop
.Ldj7_jobend:
	s_branch .Ldj7_disp
.Ldj7_done:
	s_mov_b64 exec, s[98:99]
	s_mov_b64 s[98:99], exec
	s_mov_b64 exec, -1
	v_readlane_b32 s2, v254, 0
	v_readlane_b32 s3, v255, 24
	s_load_dword s4, s[86:87], 0xc0
	s_load_dwordx2 s[6:7], s[86:87], 0x10
	s_load_dwordx2 s[88:89], s[86:87], 0xb0
	s_waitcnt lgkmcnt(0)
	s_cmp_eq_u32 s3, 1
	s_cbranch_scc0 .Ldck_sel0
	s_mov_b32 s91, 0x24000
	s_mov_b32 s79, 0x30000
	s_branch .Ldck_go
